# placement: 64-byte alignment of the four big GEMM K-loop heads
# baseline (speedup 1.0000x reference)
; template <class Epi, bool ALIGN_EPI>
; __device__ __forceinline__ void gemm_phase(LAS unsigned char* lds, const Gemm g, const Order& S, const Epi& E, const int wave_id) {
;     ...
;         const char* nA = has_next ? (const char*)g.A + (size_t)nxt.z * g.sAz + (size_t)nxt.pm * 2 * hstepA + (size_t)nxt.k0 * 2 : cA;
;         const char* nB = has_next ? (const char*)g.Bt + (size_t)nxt.z * g.sBz + (size_t)nxt.pn * 2 * hstepB + (size_t)nxt.k0 * 2 : cB;
;         const int nt = cur.nt;
;         for (int t = 0; t < nt; t += 2) {
;             const bool last = (t == nt - 2);
;             const char* a1 = cA + (size_t)(t + 1) * kstep;
;             const char* a2 = last ? nA : cA + (size_t)(t + 2) * kstep; const char* b2 = last ? nB : cB + (size_t)(t + 2) * kstep;
;             const char* a3 = a2 + kstep; const char* b3 = b2 + kstep;
;     ...
;         for (int a = 0; a < 2; ++a)
; #pragma unroll
;             for (int b = 0; b < 2; ++b)
; #pragma unroll
;                 for (int m = 0; m < 4; ++m)
; #pragma unroll
;                     for (int n = 0; n < 2; ++n) acc[a][b][m][n] = (f32x4){0.f, 0.f, 0.f, 0.f};
;         cur = nxt; cA = nA; cB = nB; ++ui;
.LBB0_409:
	s_ashr_i32 s37, s36, 31
	s_lshl_b64 s[38:39], s[36:37], 19
	s_add_u32 s38, s53, s38
	s_addc_u32 s39, s54, s39
	s_and_b64 s[40:41], s[0:1], exec
	s_cselect_b32 s3, s39, s5
	s_cselect_b32 s37, s38, s4
	s_ashr_i32 s35, s34, 31
	s_lshl_b64 s[40:41], s[34:35], 19
	s_add_u32 s40, s55, s40
	s_addc_u32 s41, s56, s41
	s_and_b64 s[44:45], s[0:1], exec
	s_cselect_b32 s35, s41, s7
	s_cselect_b32 s43, s40, s6
	s_add_u32 s4, s4, 0x40080
	s_addc_u32 s5, s5, 0
	s_add_u32 s46, s6, 0x100
	v_mov_b32_e32 v0, 0
	s_addc_u32 s47, s7, 0
	s_mov_b32 s48, -2
	v_mov_b32_e32 v1, v0
	v_mov_b32_e32 v2, v0
	v_mov_b32_e32 v3, v0
	v_mov_b32_e32 v8, v0
	v_mov_b32_e32 v9, v0
	v_mov_b32_e32 v10, v0
	v_mov_b32_e32 v11, v0
	v_mov_b32_e32 v16, v0
	v_mov_b32_e32 v17, v0
	v_mov_b32_e32 v18, v0
	v_mov_b32_e32 v19, v0
	v_mov_b32_e32 v24, v0
	v_mov_b32_e32 v25, v0
	v_mov_b32_e32 v26, v0
	v_mov_b32_e32 v27, v0
	v_mov_b32_e32 v32, v0
	v_mov_b32_e32 v33, v0
	v_mov_b32_e32 v34, v0
	v_mov_b32_e32 v35, v0
	v_mov_b32_e32 v40, v0
	v_mov_b32_e32 v41, v0
	v_mov_b32_e32 v42, v0
	v_mov_b32_e32 v43, v0
	v_mov_b32_e32 v48, v0
	v_mov_b32_e32 v49, v0
	v_mov_b32_e32 v50, v0
	v_mov_b32_e32 v51, v0
	v_mov_b32_e32 v56, v0
	v_mov_b32_e32 v57, v0
	v_mov_b32_e32 v58, v0
	v_mov_b32_e32 v59, v0
	v_mov_b32_e32 v4, v0
	v_mov_b32_e32 v5, v0
	v_mov_b32_e32 v6, v0
	v_mov_b32_e32 v7, v0
	v_mov_b32_e32 v12, v0
	v_mov_b32_e32 v13, v0
	v_mov_b32_e32 v14, v0
	v_mov_b32_e32 v15, v0
	v_mov_b32_e32 v20, v0
	v_mov_b32_e32 v21, v0
	v_mov_b32_e32 v22, v0
	v_mov_b32_e32 v23, v0
	v_mov_b32_e32 v28, v0
	v_mov_b32_e32 v29, v0
	v_mov_b32_e32 v30, v0
	v_mov_b32_e32 v31, v0
	v_mov_b32_e32 v36, v0
	v_mov_b32_e32 v37, v0
	v_mov_b32_e32 v38, v0
	v_mov_b32_e32 v39, v0
	v_mov_b32_e32 v44, v0
	v_mov_b32_e32 v45, v0
	v_mov_b32_e32 v46, v0
	v_mov_b32_e32 v47, v0
	v_mov_b32_e32 v52, v0
	v_mov_b32_e32 v53, v0
	v_mov_b32_e32 v54, v0
	v_mov_b32_e32 v55, v0
	v_mov_b32_e32 v60, v0
	v_mov_b32_e32 v61, v0
	v_mov_b32_e32 v62, v0
	v_mov_b32_e32 v63, v0
	v_mov_b32_e32 v64, v0
	v_mov_b32_e32 v65, v0
	v_mov_b32_e32 v66, v0
	v_mov_b32_e32 v67, v0
	v_mov_b32_e32 v72, v0
	v_mov_b32_e32 v73, v0
	v_mov_b32_e32 v74, v0
	v_mov_b32_e32 v75, v0
	v_mov_b32_e32 v80, v0
	v_mov_b32_e32 v81, v0
	v_mov_b32_e32 v82, v0
	v_mov_b32_e32 v83, v0
	v_mov_b32_e32 v88, v0
	v_mov_b32_e32 v89, v0
	v_mov_b32_e32 v90, v0
	v_mov_b32_e32 v91, v0
	v_mov_b32_e32 v96, v0
	v_mov_b32_e32 v97, v0
	v_mov_b32_e32 v98, v0
	v_mov_b32_e32 v99, v0
	v_mov_b32_e32 v104, v0
	v_mov_b32_e32 v105, v0
	v_mov_b32_e32 v106, v0
	v_mov_b32_e32 v107, v0
	v_mov_b32_e32 v112, v0
	v_mov_b32_e32 v113, v0
	v_mov_b32_e32 v114, v0
	v_mov_b32_e32 v115, v0
	v_mov_b32_e32 v120, v0
	v_mov_b32_e32 v121, v0
	v_mov_b32_e32 v122, v0
	v_mov_b32_e32 v123, v0
	v_mov_b32_e32 v68, v0
	v_mov_b32_e32 v69, v0
	v_mov_b32_e32 v70, v0
	v_mov_b32_e32 v71, v0
	v_mov_b32_e32 v76, v0
	v_mov_b32_e32 v77, v0
	v_mov_b32_e32 v78, v0
	v_mov_b32_e32 v79, v0
	v_mov_b32_e32 v84, v0
	v_mov_b32_e32 v85, v0
	v_mov_b32_e32 v86, v0
	v_mov_b32_e32 v87, v0
	v_mov_b32_e32 v92, v0
	v_mov_b32_e32 v93, v0
	v_mov_b32_e32 v94, v0
	v_mov_b32_e32 v95, v0
	v_mov_b32_e32 v100, v0
	v_mov_b32_e32 v101, v0
	v_mov_b32_e32 v102, v0
	v_mov_b32_e32 v103, v0
	v_mov_b32_e32 v108, v0
	v_mov_b32_e32 v109, v0
	v_mov_b32_e32 v110, v0
	v_mov_b32_e32 v111, v0
	v_mov_b32_e32 v116, v0
	v_mov_b32_e32 v117, v0
	v_mov_b32_e32 v118, v0
	v_mov_b32_e32 v119, v0
	v_mov_b32_e32 v124, v0
	v_mov_b32_e32 v125, v0
	v_mov_b32_e32 v126, v0
	v_mov_b32_e32 v127, v0
	.p2align 6

; template <class Epi, bool ALIGN_EPI>
; __device__ __forceinline__ void gemm_phase(LAS unsigned char* lds, const Gemm g, const Order& S, const Epi& E, const int wave_id) {
;     ...
;         const int nt = cur.nt;
;         for (int t = 0; t < nt; t += 2) {
;             const bool last = (t == nt - 2);
;             const char* a1 = cA + (size_t)(t + 1) * kstep;
;             const char* a2 = last ? nA : cA + (size_t)(t + 2) * kstep; const char* b2 = last ? nB : cB + (size_t)(t + 2) * kstep;
;             const char* a3 = a2 + kstep; const char* b3 = b2 + kstep;
;     ...
;         for (int a = 0; a < 2; ++a)
; #pragma unroll
;             for (int b = 0; b < 2; ++b)
; #pragma unroll
;                 for (int m = 0; m < 4; ++m)
; #pragma unroll
;                     for (int n = 0; n < 2; ++n) acc[a][b][m][n] = (f32x4){0.f, 0.f, 0.f, 0.f};
;         cur = nxt; cA = nA; cB = nB; ++ui;
.LBB0_1435:
	s_add_i32 s5, s64, -2
	s_add_u32 s2, s40, 0x40080
	s_addc_u32 s3, s41, 0
	s_add_u32 s25, s38, 0x100
	v_mov_b32_e32 v0, 0
	s_addc_u32 s27, s39, 0
	s_mov_b32 s29, 0
	v_mov_b32_e32 v1, v0
	v_mov_b32_e32 v2, v0
	v_mov_b32_e32 v3, v0
	v_mov_b32_e32 v4, v0
	v_mov_b32_e32 v5, v0
	v_mov_b32_e32 v6, v0
	v_mov_b32_e32 v7, v0
	v_mov_b32_e32 v16, v0
	v_mov_b32_e32 v17, v0
	v_mov_b32_e32 v18, v0
	v_mov_b32_e32 v19, v0
	v_mov_b32_e32 v20, v0
	v_mov_b32_e32 v21, v0
	v_mov_b32_e32 v22, v0
	v_mov_b32_e32 v23, v0
	v_mov_b32_e32 v32, v0
	v_mov_b32_e32 v33, v0
	v_mov_b32_e32 v34, v0
	v_mov_b32_e32 v35, v0
	v_mov_b32_e32 v36, v0
	v_mov_b32_e32 v37, v0
	v_mov_b32_e32 v38, v0
	v_mov_b32_e32 v39, v0
	v_mov_b32_e32 v48, v0
	v_mov_b32_e32 v49, v0
	v_mov_b32_e32 v50, v0
	v_mov_b32_e32 v51, v0
	v_mov_b32_e32 v52, v0
	v_mov_b32_e32 v53, v0
	v_mov_b32_e32 v54, v0
	v_mov_b32_e32 v55, v0
	v_mov_b32_e32 v8, v0
	v_mov_b32_e32 v9, v0
	v_mov_b32_e32 v10, v0
	v_mov_b32_e32 v11, v0
	v_mov_b32_e32 v12, v0
	v_mov_b32_e32 v13, v0
	v_mov_b32_e32 v14, v0
	v_mov_b32_e32 v15, v0
	v_mov_b32_e32 v24, v0
	v_mov_b32_e32 v25, v0
	v_mov_b32_e32 v26, v0
	v_mov_b32_e32 v27, v0
	v_mov_b32_e32 v28, v0
	v_mov_b32_e32 v29, v0
	v_mov_b32_e32 v30, v0
	v_mov_b32_e32 v31, v0
	v_mov_b32_e32 v40, v0
	v_mov_b32_e32 v41, v0
	v_mov_b32_e32 v42, v0
	v_mov_b32_e32 v43, v0
	v_mov_b32_e32 v44, v0
	v_mov_b32_e32 v45, v0
	v_mov_b32_e32 v46, v0
	v_mov_b32_e32 v47, v0
	v_mov_b32_e32 v56, v0
	v_mov_b32_e32 v57, v0
	v_mov_b32_e32 v58, v0
	v_mov_b32_e32 v59, v0
	v_mov_b32_e32 v60, v0
	v_mov_b32_e32 v61, v0
	v_mov_b32_e32 v62, v0
	v_mov_b32_e32 v63, v0
	v_mov_b32_e32 v64, v0
	v_mov_b32_e32 v65, v0
	v_mov_b32_e32 v66, v0
	v_mov_b32_e32 v67, v0
	v_mov_b32_e32 v68, v0
	v_mov_b32_e32 v69, v0
	v_mov_b32_e32 v70, v0
	v_mov_b32_e32 v71, v0
	v_mov_b32_e32 v80, v0
	v_mov_b32_e32 v81, v0
	v_mov_b32_e32 v82, v0
	v_mov_b32_e32 v83, v0
	v_mov_b32_e32 v84, v0
	v_mov_b32_e32 v85, v0
	v_mov_b32_e32 v86, v0
	v_mov_b32_e32 v87, v0
	v_mov_b32_e32 v96, v0
	v_mov_b32_e32 v97, v0
	v_mov_b32_e32 v98, v0
	v_mov_b32_e32 v99, v0
	v_mov_b32_e32 v100, v0
	v_mov_b32_e32 v101, v0
	v_mov_b32_e32 v102, v0
	v_mov_b32_e32 v103, v0
	v_mov_b32_e32 v112, v0
	v_mov_b32_e32 v113, v0
	v_mov_b32_e32 v114, v0
	v_mov_b32_e32 v115, v0
	v_mov_b32_e32 v116, v0
	v_mov_b32_e32 v117, v0
	v_mov_b32_e32 v118, v0
	v_mov_b32_e32 v119, v0
	v_mov_b32_e32 v72, v0
	v_mov_b32_e32 v73, v0
	v_mov_b32_e32 v74, v0
	v_mov_b32_e32 v75, v0
	v_mov_b32_e32 v76, v0
	v_mov_b32_e32 v77, v0
	v_mov_b32_e32 v78, v0
	v_mov_b32_e32 v79, v0
	v_mov_b32_e32 v88, v0
	v_mov_b32_e32 v89, v0
	v_mov_b32_e32 v90, v0
	v_mov_b32_e32 v91, v0
	v_mov_b32_e32 v92, v0
	v_mov_b32_e32 v93, v0
	v_mov_b32_e32 v94, v0
	v_mov_b32_e32 v95, v0
	v_mov_b32_e32 v104, v0
	v_mov_b32_e32 v105, v0
	v_mov_b32_e32 v106, v0
	v_mov_b32_e32 v107, v0
	v_mov_b32_e32 v108, v0
	v_mov_b32_e32 v109, v0
	v_mov_b32_e32 v110, v0
	v_mov_b32_e32 v111, v0
	v_mov_b32_e32 v120, v0
	v_mov_b32_e32 v121, v0
	v_mov_b32_e32 v122, v0
	v_mov_b32_e32 v123, v0
	v_mov_b32_e32 v124, v0
	v_mov_b32_e32 v125, v0
	v_mov_b32_e32 v126, v0
	v_mov_b32_e32 v127, v0
	.p2align 6

; template <class Epi, bool ALIGN_EPI>
; __device__ __forceinline__ void gemm_phase(LAS unsigned char* lds, const Gemm g, const Order& S, const Epi& E, const int wave_id) {
;     ...
;         const char* nA = has_next ? (const char*)g.A + (size_t)nxt.z * g.sAz + (size_t)nxt.pm * 2 * hstepA + (size_t)nxt.k0 * 2 : cA;
;         const char* nB = has_next ? (const char*)g.Bt + (size_t)nxt.z * g.sBz + (size_t)nxt.pn * 2 * hstepB + (size_t)nxt.k0 * 2 : cB;
;         const int nt = cur.nt;
;         for (int t = 0; t < nt; t += 2) {
;             const bool last = (t == nt - 2);
;             const char* a1 = cA + (size_t)(t + 1) * kstep;
;             const char* a2 = last ? nA : cA + (size_t)(t + 2) * kstep; const char* b2 = last ? nB : cB + (size_t)(t + 2) * kstep;
;             const char* a3 = a2 + kstep; const char* b3 = b2 + kstep;
;     ...
;         for (int a = 0; a < 2; ++a)
; #pragma unroll
;             for (int b = 0; b < 2; ++b)
; #pragma unroll
;                 for (int m = 0; m < 4; ++m)
; #pragma unroll
;                     for (int n = 0; n < 2; ++n) acc[a][b][m][n] = (f32x4){0.f, 0.f, 0.f, 0.f};
;         cur = nxt; cA = nA; cB = nB; ++ui;
.LBB0_1788:
	s_ashr_i32 s13, s12, 31
	s_lshl_b64 s[14:15], s[12:13], 19
	s_add_u32 s14, s27, s14
	s_addc_u32 s15, s28, s15
	s_and_b64 s[16:17], s[0:1], exec
	s_cselect_b32 s13, s15, s19
	s_cselect_b32 s46, s14, s18
	s_ashr_i32 s11, s10, 31
	s_lshl_b64 s[16:17], s[10:11], 19
	s_add_u32 s16, s29, s16
	s_addc_u32 s17, s30, s17
	s_and_b64 s[22:23], s[0:1], exec
	s_cselect_b32 s11, s17, s21
	s_cselect_b32 s47, s16, s20
	s_add_u32 s18, s18, 0x40080
	s_addc_u32 s19, s19, 0
	s_add_u32 s48, s20, 0x100
	v_mov_b32_e32 v0, 0
	s_addc_u32 s49, s21, 0
	s_mov_b32 s50, -2
	v_mov_b32_e32 v1, v0
	v_mov_b32_e32 v2, v0
	v_mov_b32_e32 v3, v0
	v_mov_b32_e32 v8, v0
	v_mov_b32_e32 v9, v0
	v_mov_b32_e32 v10, v0
	v_mov_b32_e32 v11, v0
	v_mov_b32_e32 v16, v0
	v_mov_b32_e32 v17, v0
	v_mov_b32_e32 v18, v0
	v_mov_b32_e32 v19, v0
	v_mov_b32_e32 v24, v0
	v_mov_b32_e32 v25, v0
	v_mov_b32_e32 v26, v0
	v_mov_b32_e32 v27, v0
	v_mov_b32_e32 v32, v0
	v_mov_b32_e32 v33, v0
	v_mov_b32_e32 v34, v0
	v_mov_b32_e32 v35, v0
	v_mov_b32_e32 v40, v0
	v_mov_b32_e32 v41, v0
	v_mov_b32_e32 v42, v0
	v_mov_b32_e32 v43, v0
	v_mov_b32_e32 v48, v0
	v_mov_b32_e32 v49, v0
	v_mov_b32_e32 v50, v0
	v_mov_b32_e32 v51, v0
	v_mov_b32_e32 v56, v0
	v_mov_b32_e32 v57, v0
	v_mov_b32_e32 v58, v0
	v_mov_b32_e32 v59, v0
	v_mov_b32_e32 v4, v0
	v_mov_b32_e32 v5, v0
	v_mov_b32_e32 v6, v0
	v_mov_b32_e32 v7, v0
	v_mov_b32_e32 v12, v0
	v_mov_b32_e32 v13, v0
	v_mov_b32_e32 v14, v0
	v_mov_b32_e32 v15, v0
	v_mov_b32_e32 v20, v0
	v_mov_b32_e32 v21, v0
	v_mov_b32_e32 v22, v0
	v_mov_b32_e32 v23, v0
	v_mov_b32_e32 v28, v0
	v_mov_b32_e32 v29, v0
	v_mov_b32_e32 v30, v0
	v_mov_b32_e32 v31, v0
	v_mov_b32_e32 v36, v0
	v_mov_b32_e32 v37, v0
	v_mov_b32_e32 v38, v0
	v_mov_b32_e32 v39, v0
	v_mov_b32_e32 v44, v0
	v_mov_b32_e32 v45, v0
	v_mov_b32_e32 v46, v0
	v_mov_b32_e32 v47, v0
	v_mov_b32_e32 v52, v0
	v_mov_b32_e32 v53, v0
	v_mov_b32_e32 v54, v0
	v_mov_b32_e32 v55, v0
	v_mov_b32_e32 v60, v0
	v_mov_b32_e32 v61, v0
	v_mov_b32_e32 v62, v0
	v_mov_b32_e32 v63, v0
	v_mov_b32_e32 v64, v0
	v_mov_b32_e32 v65, v0
	v_mov_b32_e32 v66, v0
	v_mov_b32_e32 v67, v0
	v_mov_b32_e32 v72, v0
	v_mov_b32_e32 v73, v0
	v_mov_b32_e32 v74, v0
	v_mov_b32_e32 v75, v0
	v_mov_b32_e32 v80, v0
	v_mov_b32_e32 v81, v0
	v_mov_b32_e32 v82, v0
	v_mov_b32_e32 v83, v0
	v_mov_b32_e32 v88, v0
	v_mov_b32_e32 v89, v0
	v_mov_b32_e32 v90, v0
	v_mov_b32_e32 v91, v0
	v_mov_b32_e32 v96, v0
	v_mov_b32_e32 v97, v0
	v_mov_b32_e32 v98, v0
	v_mov_b32_e32 v99, v0
	v_mov_b32_e32 v104, v0
	v_mov_b32_e32 v105, v0
	v_mov_b32_e32 v106, v0
	v_mov_b32_e32 v107, v0
	v_mov_b32_e32 v112, v0
	v_mov_b32_e32 v113, v0
	v_mov_b32_e32 v114, v0
	v_mov_b32_e32 v115, v0
	v_mov_b32_e32 v120, v0
	v_mov_b32_e32 v121, v0
	v_mov_b32_e32 v122, v0
	v_mov_b32_e32 v123, v0
	v_mov_b32_e32 v68, v0
	v_mov_b32_e32 v69, v0
	v_mov_b32_e32 v70, v0
	v_mov_b32_e32 v71, v0
	v_mov_b32_e32 v76, v0
	v_mov_b32_e32 v77, v0
	v_mov_b32_e32 v78, v0
	v_mov_b32_e32 v79, v0
	v_mov_b32_e32 v84, v0
	v_mov_b32_e32 v85, v0
	v_mov_b32_e32 v86, v0
	v_mov_b32_e32 v87, v0
	v_mov_b32_e32 v92, v0
	v_mov_b32_e32 v93, v0
	v_mov_b32_e32 v94, v0
	v_mov_b32_e32 v95, v0
	v_mov_b32_e32 v100, v0
	v_mov_b32_e32 v101, v0
	v_mov_b32_e32 v102, v0
	v_mov_b32_e32 v103, v0
	v_mov_b32_e32 v108, v0
	v_mov_b32_e32 v109, v0
	v_mov_b32_e32 v110, v0
	v_mov_b32_e32 v111, v0
	v_mov_b32_e32 v116, v0
	v_mov_b32_e32 v117, v0
	v_mov_b32_e32 v118, v0
	v_mov_b32_e32 v119, v0
	v_mov_b32_e32 v124, v0
	v_mov_b32_e32 v125, v0
	v_mov_b32_e32 v126, v0
	v_mov_b32_e32 v127, v0
	.p2align 6

; template <class Epi, bool ALIGN_EPI>
; __device__ __forceinline__ void gemm_phase(LAS unsigned char* lds, const Gemm g, const Order& S, const Epi& E, const int wave_id) {
;     ...
;         const int nt = cur.nt;
;         for (int t = 0; t < nt; t += 2) {
;             const bool last = (t == nt - 2);
;             const char* a1 = cA + (size_t)(t + 1) * kstep;
;             const char* a2 = last ? nA : cA + (size_t)(t + 2) * kstep; const char* b2 = last ? nB : cB + (size_t)(t + 2) * kstep;
;             const char* a3 = a2 + kstep; const char* b3 = b2 + kstep;
;     ...
;         for (int a = 0; a < 2; ++a)
; #pragma unroll
;             for (int b = 0; b < 2; ++b)
; #pragma unroll
;                 for (int m = 0; m < 4; ++m)
; #pragma unroll
;                     for (int n = 0; n < 2; ++n) acc[a][b][m][n] = (f32x4){0.f, 0.f, 0.f, 0.f};
;         cur = nxt; cA = nA; cB = nB; ++ui;
.LBB0_1878:
	s_add_i32 s17, s56, -2
	s_add_u32 s57, s24, 0x100
	v_mov_b32_e32 v0, 0
	s_addc_u32 s58, s25, 0
	s_mov_b32 s24, 0
	v_mov_b32_e32 v1, v0
	v_mov_b32_e32 v2, v0
	v_mov_b32_e32 v3, v0
	v_mov_b32_e32 v4, v0
	v_mov_b32_e32 v5, v0
	v_mov_b32_e32 v6, v0
	v_mov_b32_e32 v7, v0
	v_mov_b32_e32 v16, v0
	v_mov_b32_e32 v17, v0
	v_mov_b32_e32 v18, v0
	v_mov_b32_e32 v19, v0
	v_mov_b32_e32 v20, v0
	v_mov_b32_e32 v21, v0
	v_mov_b32_e32 v22, v0
	v_mov_b32_e32 v23, v0
	v_mov_b32_e32 v32, v0
	v_mov_b32_e32 v33, v0
	v_mov_b32_e32 v34, v0
	v_mov_b32_e32 v35, v0
	v_mov_b32_e32 v36, v0
	v_mov_b32_e32 v37, v0
	v_mov_b32_e32 v38, v0
	v_mov_b32_e32 v39, v0
	v_mov_b32_e32 v48, v0
	v_mov_b32_e32 v49, v0
	v_mov_b32_e32 v50, v0
	v_mov_b32_e32 v51, v0
	v_mov_b32_e32 v52, v0
	v_mov_b32_e32 v53, v0
	v_mov_b32_e32 v54, v0
	v_mov_b32_e32 v55, v0
	v_mov_b32_e32 v8, v0
	v_mov_b32_e32 v9, v0
	v_mov_b32_e32 v10, v0
	v_mov_b32_e32 v11, v0
	v_mov_b32_e32 v12, v0
	v_mov_b32_e32 v13, v0
	v_mov_b32_e32 v14, v0
	v_mov_b32_e32 v15, v0
	v_mov_b32_e32 v24, v0
	v_mov_b32_e32 v25, v0
	v_mov_b32_e32 v26, v0
	v_mov_b32_e32 v27, v0
	v_mov_b32_e32 v28, v0
	v_mov_b32_e32 v29, v0
	v_mov_b32_e32 v30, v0
	v_mov_b32_e32 v31, v0
	v_mov_b32_e32 v40, v0
	v_mov_b32_e32 v41, v0
	v_mov_b32_e32 v42, v0
	v_mov_b32_e32 v43, v0
	v_mov_b32_e32 v44, v0
	v_mov_b32_e32 v45, v0
	v_mov_b32_e32 v46, v0
	v_mov_b32_e32 v47, v0
	v_mov_b32_e32 v56, v0
	v_mov_b32_e32 v57, v0
	v_mov_b32_e32 v58, v0
	v_mov_b32_e32 v59, v0
	v_mov_b32_e32 v60, v0
	v_mov_b32_e32 v61, v0
	v_mov_b32_e32 v62, v0
	v_mov_b32_e32 v63, v0
	v_mov_b32_e32 v64, v0
	v_mov_b32_e32 v65, v0
	v_mov_b32_e32 v66, v0
	v_mov_b32_e32 v67, v0
	v_mov_b32_e32 v68, v0
	v_mov_b32_e32 v69, v0
	v_mov_b32_e32 v70, v0
	v_mov_b32_e32 v71, v0
	v_mov_b32_e32 v80, v0
	v_mov_b32_e32 v81, v0
	v_mov_b32_e32 v82, v0
	v_mov_b32_e32 v83, v0
	v_mov_b32_e32 v84, v0
	v_mov_b32_e32 v85, v0
	v_mov_b32_e32 v86, v0
	v_mov_b32_e32 v87, v0
	v_mov_b32_e32 v96, v0
	v_mov_b32_e32 v97, v0
	v_mov_b32_e32 v98, v0
	v_mov_b32_e32 v99, v0
	v_mov_b32_e32 v100, v0
	v_mov_b32_e32 v101, v0
	v_mov_b32_e32 v102, v0
	v_mov_b32_e32 v103, v0
	v_mov_b32_e32 v112, v0
	v_mov_b32_e32 v113, v0
	v_mov_b32_e32 v114, v0
	v_mov_b32_e32 v115, v0
	v_mov_b32_e32 v116, v0
	v_mov_b32_e32 v117, v0
	v_mov_b32_e32 v118, v0
	v_mov_b32_e32 v119, v0
	v_mov_b32_e32 v72, v0
	v_mov_b32_e32 v73, v0
	v_mov_b32_e32 v74, v0
	v_mov_b32_e32 v75, v0
	v_mov_b32_e32 v76, v0
	v_mov_b32_e32 v77, v0
	v_mov_b32_e32 v78, v0
	v_mov_b32_e32 v79, v0
	v_mov_b32_e32 v88, v0
	v_mov_b32_e32 v89, v0
	v_mov_b32_e32 v90, v0
	v_mov_b32_e32 v91, v0
	v_mov_b32_e32 v92, v0
	v_mov_b32_e32 v93, v0
	v_mov_b32_e32 v94, v0
	v_mov_b32_e32 v95, v0
	v_mov_b32_e32 v104, v0
	v_mov_b32_e32 v105, v0
	v_mov_b32_e32 v106, v0
	v_mov_b32_e32 v107, v0
	v_mov_b32_e32 v108, v0
	v_mov_b32_e32 v109, v0
	v_mov_b32_e32 v110, v0
	v_mov_b32_e32 v111, v0
	v_mov_b32_e32 v120, v0
	v_mov_b32_e32 v121, v0
	v_mov_b32_e32 v122, v0
	v_mov_b32_e32 v123, v0
	v_mov_b32_e32 v124, v0
	v_mov_b32_e32 v125, v0
	v_mov_b32_e32 v126, v0
	v_mov_b32_e32 v127, v0
	.p2align 6
